# phase F epilogue stores write-through (sc0 sc1)
# speedup vs baseline: 1.0004x; 1.0004x over previous
; __device__ __forceinline__ float fast_sigmoid(float x) { return __builtin_amdgcn_rcpf(1.0f + __expf(-x)); }
;     __device__ __forceinline__ void operator()(const i32x4 (&acc)[2][2][4][2], const Unit& u, int wr, int wc, int fr, int fq) const {
;         const int row0 = u.pm * BM + wr * 64 + fr, col0 = u.pn * HALF + wc * 32 + 8 * fq, brow = u.pn * BM + wc * 32 + 8 * fq;
;         const f32x4 dg0 = *(const f32x4*)(DB + brow), dg1 = *(const f32x4*)(DB + brow + 4), du0 = *(const f32x4*)(DB + brow + HALF), du1 = *(const f32x4*)(DB + brow + HALF + 4);
;         float rav[2][4];
; #pragma unroll
;         for (int ai = 0; ai < 2; ++ai)
; #pragma unroll
;             for (int m = 0; m < 4; ++m) rav[ai][m] = RA[row0 + ai * HALF + m * 16];
;         __builtin_amdgcn_sched_barrier(0);
;     ...
;                 for (int j = 0; j < 4; ++j) { const float g0 = (float)acc[ai][0][m][0][j] * ra * dg0[j], u0 = (float)acc[ai][1][m][0][j] * ra * du0[j]; hv[j] = g0 * fast_sigmoid(g0) * u0;
;                     const float g1 = (float)acc[ai][0][m][1][j] * ra * dg1[j], u1 = (float)acc[ai][1][m][1][j] * ra * du1[j]; hv[4 + j] = g1 * fast_sigmoid(g1) * u1; }
.LBB0_1594:
	v_lshl_add_u32 v160, s35, 8, v159
	v_lshl_or_b32 v36, s34, 8, v169
	v_or_b32_e32 v178, 32, v160
	v_ashrrev_i32_e32 v37, 31, v36
	v_ashrrev_i32_e32 v161, 31, v160
	v_or_b32_e32 v182, 16, v160
	v_ashrrev_i32_e32 v179, 31, v178
	v_or_b32_e32 v174, 48, v160
	v_lshl_add_u64 v[144:145], v[36:37], 2, s[18:19]
	v_lshl_add_u64 v[162:163], v[160:161], 2, s[16:17]
	v_ashrrev_i32_e32 v183, 31, v182
	v_lshl_add_u64 v[172:173], v[178:179], 2, s[16:17]
	v_ashrrev_i32_e32 v175, 31, v174
	global_load_dwordx4 v[36:39], v[144:145], off offset:16
	global_load_dwordx4 v[44:47], v[144:145], off
	global_load_dwordx4 v[140:143], v[144:145], off offset:528
	s_nop 0
	global_load_dwordx4 v[144:147], v[144:145], off offset:512
	v_lshl_add_u64 v[164:165], v[182:183], 2, s[16:17]
	v_lshl_add_u64 v[184:185], v[174:175], 2, s[16:17]
	global_load_dword v188, v[162:163], off
	global_load_dword v180, v[164:165], off
	global_load_dword v176, v[172:173], off
	s_nop 0
	global_load_dword v172, v[184:185], off
	global_load_dword v170, v[162:163], off offset:512
	global_load_dword v168, v[162:163], off offset:576
	global_load_dword v166, v[162:163], off offset:640
	global_load_dword v158, v[162:163], off offset:704
	v_lshl_or_b32 v186, s34, 7, v169
	s_movk_i32 s23, 0x5600
	v_lshlrev_b32_e32 v186, 1, v186
	v_mad_u32_u24 v186, v160, s23, v186
	v_mov_b32_e32 v178, 0xbfb8aa3b
	v_mov_b32_e32 v179, 1.0
	v_cvt_f32_i32_e32 v136, v136
	v_cvt_f32_i32_e32 v137, v137
	v_cvt_f32_i32_e32 v138, v138
	v_cvt_f32_i32_e32 v139, v139
	v_cvt_f32_i32_e32 v132, v132
	v_cvt_f32_i32_e32 v133, v133
	v_cvt_f32_i32_e32 v134, v134
	v_cvt_f32_i32_e32 v135, v135
	v_cvt_f32_i32_e32 v128, v128
	v_cvt_f32_i32_e32 v129, v129
	v_cvt_f32_i32_e32 v130, v130
	v_cvt_f32_i32_e32 v131, v131
	v_cvt_f32_i32_e32 v124, v124
	v_cvt_f32_i32_e32 v125, v125
	v_cvt_f32_i32_e32 v126, v126
	v_cvt_f32_i32_e32 v127, v127
	v_cvt_f32_i32_e32 v120, v120
	v_cvt_f32_i32_e32 v121, v121
	v_cvt_f32_i32_e32 v122, v122
	v_cvt_f32_i32_e32 v123, v123
	v_cvt_f32_i32_e32 v116, v116
	v_cvt_f32_i32_e32 v117, v117
	v_cvt_f32_i32_e32 v118, v118
	v_cvt_f32_i32_e32 v119, v119
	v_cvt_f32_i32_e32 v112, v112
	v_cvt_f32_i32_e32 v113, v113
	v_cvt_f32_i32_e32 v114, v114
	v_cvt_f32_i32_e32 v115, v115
	v_cvt_f32_i32_e32 v108, v108
	v_cvt_f32_i32_e32 v109, v109
	v_cvt_f32_i32_e32 v110, v110
	v_cvt_f32_i32_e32 v111, v111
	v_cvt_f32_i32_e32 v104, v104
	v_cvt_f32_i32_e32 v105, v105
	v_cvt_f32_i32_e32 v106, v106
	v_cvt_f32_i32_e32 v107, v107
	v_cvt_f32_i32_e32 v100, v100
	v_cvt_f32_i32_e32 v101, v101
	v_cvt_f32_i32_e32 v102, v102
	v_cvt_f32_i32_e32 v103, v103
	v_cvt_f32_i32_e32 v96, v96
	v_cvt_f32_i32_e32 v97, v97
	v_cvt_f32_i32_e32 v98, v98
	v_cvt_f32_i32_e32 v99, v99
	v_cvt_f32_i32_e32 v92, v92
	v_cvt_f32_i32_e32 v93, v93
	v_cvt_f32_i32_e32 v94, v94
	v_cvt_f32_i32_e32 v95, v95
	v_cvt_f32_i32_e32 v88, v88
	v_cvt_f32_i32_e32 v89, v89
	v_cvt_f32_i32_e32 v90, v90
	v_cvt_f32_i32_e32 v91, v91
	v_cvt_f32_i32_e32 v84, v84
	v_cvt_f32_i32_e32 v85, v85
	v_cvt_f32_i32_e32 v86, v86
	v_cvt_f32_i32_e32 v87, v87
	v_cvt_f32_i32_e32 v80, v80
	v_cvt_f32_i32_e32 v81, v81
	v_cvt_f32_i32_e32 v82, v82
	v_cvt_f32_i32_e32 v83, v83
	v_cvt_f32_i32_e32 v76, v76
	v_cvt_f32_i32_e32 v77, v77
	v_cvt_f32_i32_e32 v78, v78
	v_cvt_f32_i32_e32 v79, v79
	v_cvt_f32_i32_e32 v72, v72
	v_cvt_f32_i32_e32 v73, v73
	v_cvt_f32_i32_e32 v74, v74
	v_cvt_f32_i32_e32 v75, v75
	v_cvt_f32_i32_e32 v68, v68
	v_cvt_f32_i32_e32 v69, v69
	v_cvt_f32_i32_e32 v70, v70
	v_cvt_f32_i32_e32 v71, v71
	v_cvt_f32_i32_e32 v64, v64
	v_cvt_f32_i32_e32 v65, v65
	v_cvt_f32_i32_e32 v66, v66
	v_cvt_f32_i32_e32 v67, v67
	v_cvt_f32_i32_e32 v60, v60
	v_cvt_f32_i32_e32 v61, v61
	v_cvt_f32_i32_e32 v62, v62
	v_cvt_f32_i32_e32 v63, v63
	v_cvt_f32_i32_e32 v56, v56
	v_cvt_f32_i32_e32 v57, v57
	v_cvt_f32_i32_e32 v58, v58
	v_cvt_f32_i32_e32 v59, v59
	v_cvt_f32_i32_e32 v52, v52
	v_cvt_f32_i32_e32 v53, v53
	v_cvt_f32_i32_e32 v54, v54
	v_cvt_f32_i32_e32 v55, v55
	v_cvt_f32_i32_e32 v48, v48
	v_cvt_f32_i32_e32 v49, v49
	v_cvt_f32_i32_e32 v50, v50
	v_cvt_f32_i32_e32 v51, v51
	v_cvt_f32_i32_e32 v40, v40
	v_cvt_f32_i32_e32 v41, v41
	v_cvt_f32_i32_e32 v42, v42
	v_cvt_f32_i32_e32 v43, v43
	v_cvt_f32_i32_e32 v32, v32
	v_cvt_f32_i32_e32 v33, v33
	v_cvt_f32_i32_e32 v34, v34
	v_cvt_f32_i32_e32 v35, v35
	v_cvt_f32_i32_e32 v28, v28
	v_cvt_f32_i32_e32 v29, v29
	v_cvt_f32_i32_e32 v30, v30
	v_cvt_f32_i32_e32 v31, v31
	v_cvt_f32_i32_e32 v24, v24
	v_cvt_f32_i32_e32 v25, v25
	v_cvt_f32_i32_e32 v26, v26
	v_cvt_f32_i32_e32 v27, v27
	v_cvt_f32_i32_e32 v20, v20
	v_cvt_f32_i32_e32 v21, v21
	v_cvt_f32_i32_e32 v22, v22
	v_cvt_f32_i32_e32 v23, v23
	v_cvt_f32_i32_e32 v16, v16
	v_cvt_f32_i32_e32 v17, v17
	v_cvt_f32_i32_e32 v18, v18
	v_cvt_f32_i32_e32 v19, v19
	v_cvt_f32_i32_e32 v12, v12
	v_cvt_f32_i32_e32 v13, v13
	v_cvt_f32_i32_e32 v14, v14
	v_cvt_f32_i32_e32 v15, v15
	v_cvt_f32_i32_e32 v8, v8
	v_cvt_f32_i32_e32 v9, v9
	v_cvt_f32_i32_e32 v10, v10
	v_cvt_f32_i32_e32 v11, v11
	v_cvt_f32_i32_e32 v4, v4
	v_cvt_f32_i32_e32 v5, v5
	v_cvt_f32_i32_e32 v6, v6
	v_cvt_f32_i32_e32 v7, v7
	s_waitcnt vmcnt(0)
; __device__ __forceinline__ unsigned cvt_pk_bf16(float lo, float hi) { unsigned r; asm volatile("v_cvt_pk_bf16_f32 %0, %1, %2" : "=v"(r) : "v"(lo), "v"(hi)); return r; }
; __device__ __forceinline__ float fast_sigmoid(float x) { return __builtin_amdgcn_rcpf(1.0f + __expf(-x)); }
;     __device__ __forceinline__ void operator()(const i32x4 (&acc)[2][2][4][2], const Unit& u, int wr, int wc, int fr, int fq) const {
;     ...
;         for (int ai = 0; ai < 2; ++ai)
; #pragma unroll
;             for (int m = 0; m < 4; ++m) { const int row = row0 + ai * HALF + m * 16; const float ra = rav[ai][m]; bf16_t* rowp = H + (size_t)row * ldh + col0;
;                 float hv[8];
; #pragma unroll
;                 for (int j = 0; j < 4; ++j) { const float g0 = (float)acc[ai][0][m][0][j] * ra * dg0[j], u0 = (float)acc[ai][1][m][0][j] * ra * du0[j]; hv[j] = g0 * fast_sigmoid(g0) * u0;
;                     const float g1 = (float)acc[ai][0][m][1][j] * ra * dg1[j], u1 = (float)acc[ai][1][m][1][j] * ra * du1[j]; hv[4 + j] = g1 * fast_sigmoid(g1) * u1; }
;                 u32x4 w; w.x = cvt_pk_bf16(hv[0], hv[1]); w.y = cvt_pk_bf16(hv[2], hv[3]); w.z = cvt_pk_bf16(hv[4], hv[5]); w.w = cvt_pk_bf16(hv[6], hv[7]);
;                 *(u32x4*)rowp = w; }
	v_pk_mul_f32 v[136:137], v[188:189], v[136:137] op_sel_hi:[0,1]
	v_pk_mul_f32 v[132:133], v[188:189], v[132:133] op_sel_hi:[0,1]
	v_pk_mul_f32 v[138:139], v[188:189], v[138:139] op_sel_hi:[0,1]
	v_pk_mul_f32 v[134:135], v[188:189], v[134:135] op_sel_hi:[0,1]
	v_pk_mul_f32 v[128:129], v[188:189], v[128:129] op_sel_hi:[0,1]
	v_pk_mul_f32 v[124:125], v[188:189], v[124:125] op_sel_hi:[0,1]
	v_pk_mul_f32 v[130:131], v[188:189], v[130:131] op_sel_hi:[0,1]
	v_pk_mul_f32 v[126:127], v[188:189], v[126:127] op_sel_hi:[0,1]
	v_pk_mul_f32 v[136:137], v[44:45], v[136:137]
	v_pk_mul_f32 v[132:133], v[144:145], v[132:133]
	v_pk_mul_f32 v[138:139], v[46:47], v[138:139]
	v_pk_mul_f32 v[134:135], v[146:147], v[134:135]
	v_pk_mul_f32 v[128:129], v[36:37], v[128:129]
	v_pk_mul_f32 v[124:125], v[140:141], v[124:125]
	v_pk_mul_f32 v[130:131], v[38:39], v[130:131]
	v_pk_mul_f32 v[126:127], v[142:143], v[126:127]
	v_pk_mul_f32 v[160:161], v[178:179], v[136:137] op_sel_hi:[0,1]
	v_pk_mul_f32 v[162:163], v[178:179], v[138:139] op_sel_hi:[0,1]
	v_exp_f32_e32 v160, v160
	v_exp_f32_e32 v161, v161
	v_exp_f32_e32 v162, v162
	v_exp_f32_e32 v163, v163
	v_pk_add_f32 v[160:161], v[178:179], v[160:161] op_sel:[1,0] op_sel_hi:[1,1]
	v_pk_add_f32 v[162:163], v[178:179], v[162:163] op_sel:[1,0] op_sel_hi:[1,1]
	v_rcp_f32_e32 v160, v160
	v_rcp_f32_e32 v161, v161
	v_rcp_f32_e32 v162, v162
	v_rcp_f32_e32 v163, v163
	v_pk_mul_f32 v[136:137], v[136:137], v[160:161]
	v_pk_mul_f32 v[138:139], v[138:139], v[162:163]
	v_pk_mul_f32 v[136:137], v[132:133], v[136:137]
	v_pk_mul_f32 v[138:139], v[134:135], v[138:139]
	v_pk_mul_f32 v[160:161], v[178:179], v[128:129] op_sel_hi:[0,1]
	v_pk_mul_f32 v[162:163], v[178:179], v[130:131] op_sel_hi:[0,1]
	v_exp_f32_e32 v160, v160
	v_exp_f32_e32 v161, v161
	v_exp_f32_e32 v162, v162
	v_exp_f32_e32 v163, v163
	v_pk_add_f32 v[160:161], v[178:179], v[160:161] op_sel:[1,0] op_sel_hi:[1,1]
	v_pk_add_f32 v[162:163], v[178:179], v[162:163] op_sel:[1,0] op_sel_hi:[1,1]
	v_rcp_f32_e32 v160, v160
	v_rcp_f32_e32 v161, v161
	v_rcp_f32_e32 v162, v162
	v_rcp_f32_e32 v163, v163
	v_pk_mul_f32 v[128:129], v[128:129], v[160:161]
	v_pk_mul_f32 v[130:131], v[130:131], v[162:163]
	v_pk_mul_f32 v[128:129], v[124:125], v[128:129]
	v_pk_mul_f32 v[130:131], v[126:127], v[130:131]
	v_cvt_pk_bf16_f32 v136, v136, v137
	v_cvt_pk_bf16_f32 v137, v138, v139
	v_cvt_pk_bf16_f32 v138, v128, v129
	v_cvt_pk_bf16_f32 v139, v130, v131
	global_store_dwordx4 v186, v[136:139], s[14:15] sc0 sc1
	v_pk_mul_f32 v[120:121], v[180:181], v[120:121] op_sel_hi:[0,1]
	v_pk_mul_f32 v[116:117], v[180:181], v[116:117] op_sel_hi:[0,1]
	v_pk_mul_f32 v[122:123], v[180:181], v[122:123] op_sel_hi:[0,1]
	v_pk_mul_f32 v[118:119], v[180:181], v[118:119] op_sel_hi:[0,1]
	v_pk_mul_f32 v[112:113], v[180:181], v[112:113] op_sel_hi:[0,1]
	v_pk_mul_f32 v[108:109], v[180:181], v[108:109] op_sel_hi:[0,1]
	v_pk_mul_f32 v[114:115], v[180:181], v[114:115] op_sel_hi:[0,1]
	v_pk_mul_f32 v[110:111], v[180:181], v[110:111] op_sel_hi:[0,1]
	v_pk_mul_f32 v[120:121], v[44:45], v[120:121]
	v_pk_mul_f32 v[116:117], v[144:145], v[116:117]
	v_pk_mul_f32 v[122:123], v[46:47], v[122:123]
	v_pk_mul_f32 v[118:119], v[146:147], v[118:119]
	v_pk_mul_f32 v[112:113], v[36:37], v[112:113]
	v_pk_mul_f32 v[108:109], v[140:141], v[108:109]
	v_pk_mul_f32 v[114:115], v[38:39], v[114:115]
	v_pk_mul_f32 v[110:111], v[142:143], v[110:111]
	v_pk_mul_f32 v[160:161], v[178:179], v[120:121] op_sel_hi:[0,1]
	v_pk_mul_f32 v[162:163], v[178:179], v[122:123] op_sel_hi:[0,1]
	v_exp_f32_e32 v160, v160
	v_exp_f32_e32 v161, v161
	v_exp_f32_e32 v162, v162
	v_exp_f32_e32 v163, v163
	v_pk_add_f32 v[160:161], v[178:179], v[160:161] op_sel:[1,0] op_sel_hi:[1,1]
	v_pk_add_f32 v[162:163], v[178:179], v[162:163] op_sel:[1,0] op_sel_hi:[1,1]
	v_rcp_f32_e32 v160, v160
	v_rcp_f32_e32 v161, v161
	v_rcp_f32_e32 v162, v162
	v_rcp_f32_e32 v163, v163
	v_pk_mul_f32 v[120:121], v[120:121], v[160:161]
	v_pk_mul_f32 v[122:123], v[122:123], v[162:163]
	v_pk_mul_f32 v[120:121], v[116:117], v[120:121]
	v_pk_mul_f32 v[122:123], v[118:119], v[122:123]
	v_pk_mul_f32 v[160:161], v[178:179], v[112:113] op_sel_hi:[0,1]
	v_pk_mul_f32 v[162:163], v[178:179], v[114:115] op_sel_hi:[0,1]
	v_exp_f32_e32 v160, v160
	v_exp_f32_e32 v161, v161
	v_exp_f32_e32 v162, v162
	v_exp_f32_e32 v163, v163
	v_pk_add_f32 v[160:161], v[178:179], v[160:161] op_sel:[1,0] op_sel_hi:[1,1]
	v_pk_add_f32 v[162:163], v[178:179], v[162:163] op_sel:[1,0] op_sel_hi:[1,1]
	v_rcp_f32_e32 v160, v160
	v_rcp_f32_e32 v161, v161
	v_rcp_f32_e32 v162, v162
	v_rcp_f32_e32 v163, v163
	v_pk_mul_f32 v[112:113], v[112:113], v[160:161]
	v_pk_mul_f32 v[114:115], v[114:115], v[162:163]
	v_pk_mul_f32 v[112:113], v[108:109], v[112:113]
	v_pk_mul_f32 v[114:115], v[110:111], v[114:115]
	v_cvt_pk_bf16_f32 v120, v120, v121
	v_cvt_pk_bf16_f32 v121, v122, v123
	v_cvt_pk_bf16_f32 v122, v112, v113
	v_cvt_pk_bf16_f32 v123, v114, v115
	v_add_u32_e32 v187, 0x56000, v186
	global_store_dwordx4 v187, v[120:123], s[14:15] sc0 sc1
	v_pk_mul_f32 v[104:105], v[176:177], v[104:105] op_sel_hi:[0,1]
	v_pk_mul_f32 v[100:101], v[176:177], v[100:101] op_sel_hi:[0,1]
	v_pk_mul_f32 v[106:107], v[176:177], v[106:107] op_sel_hi:[0,1]
	v_pk_mul_f32 v[102:103], v[176:177], v[102:103] op_sel_hi:[0,1]
	v_pk_mul_f32 v[96:97], v[176:177], v[96:97] op_sel_hi:[0,1]
	v_pk_mul_f32 v[92:93], v[176:177], v[92:93] op_sel_hi:[0,1]
	v_pk_mul_f32 v[98:99], v[176:177], v[98:99] op_sel_hi:[0,1]
	v_pk_mul_f32 v[94:95], v[176:177], v[94:95] op_sel_hi:[0,1]
	v_pk_mul_f32 v[104:105], v[44:45], v[104:105]
	v_pk_mul_f32 v[100:101], v[144:145], v[100:101]
	v_pk_mul_f32 v[106:107], v[46:47], v[106:107]
; __device__ __forceinline__ unsigned cvt_pk_bf16(float lo, float hi) { unsigned r; asm volatile("v_cvt_pk_bf16_f32 %0, %1, %2" : "=v"(r) : "v"(lo), "v"(hi)); return r; }
; __device__ __forceinline__ float fast_sigmoid(float x) { return __builtin_amdgcn_rcpf(1.0f + __expf(-x)); }
;     __device__ __forceinline__ void operator()(const i32x4 (&acc)[2][2][4][2], const Unit& u, int wr, int wc, int fr, int fq) const {
;     ...
;         for (int ai = 0; ai < 2; ++ai)
; #pragma unroll
;             for (int m = 0; m < 4; ++m) { const int row = row0 + ai * HALF + m * 16; const float ra = rav[ai][m]; bf16_t* rowp = H + (size_t)row * ldh + col0;
;                 float hv[8];
; #pragma unroll
;                 for (int j = 0; j < 4; ++j) { const float g0 = (float)acc[ai][0][m][0][j] * ra * dg0[j], u0 = (float)acc[ai][1][m][0][j] * ra * du0[j]; hv[j] = g0 * fast_sigmoid(g0) * u0;
;                     const float g1 = (float)acc[ai][0][m][1][j] * ra * dg1[j], u1 = (float)acc[ai][1][m][1][j] * ra * du1[j]; hv[4 + j] = g1 * fast_sigmoid(g1) * u1; }
;                 u32x4 w; w.x = cvt_pk_bf16(hv[0], hv[1]); w.y = cvt_pk_bf16(hv[2], hv[3]); w.z = cvt_pk_bf16(hv[4], hv[5]); w.w = cvt_pk_bf16(hv[6], hv[7]);
;                 *(u32x4*)rowp = w; }
	v_pk_mul_f32 v[102:103], v[146:147], v[102:103]
	v_pk_mul_f32 v[96:97], v[36:37], v[96:97]
	v_pk_mul_f32 v[92:93], v[140:141], v[92:93]
	v_pk_mul_f32 v[98:99], v[38:39], v[98:99]
	v_pk_mul_f32 v[94:95], v[142:143], v[94:95]
	v_pk_mul_f32 v[160:161], v[178:179], v[104:105] op_sel_hi:[0,1]
	v_pk_mul_f32 v[162:163], v[178:179], v[106:107] op_sel_hi:[0,1]
	v_exp_f32_e32 v160, v160
	v_exp_f32_e32 v161, v161
	v_exp_f32_e32 v162, v162
	v_exp_f32_e32 v163, v163
	v_pk_add_f32 v[160:161], v[178:179], v[160:161] op_sel:[1,0] op_sel_hi:[1,1]
	v_pk_add_f32 v[162:163], v[178:179], v[162:163] op_sel:[1,0] op_sel_hi:[1,1]
	v_rcp_f32_e32 v160, v160
	v_rcp_f32_e32 v161, v161
	v_rcp_f32_e32 v162, v162
	v_rcp_f32_e32 v163, v163
	v_pk_mul_f32 v[104:105], v[104:105], v[160:161]
	v_pk_mul_f32 v[106:107], v[106:107], v[162:163]
	v_pk_mul_f32 v[104:105], v[100:101], v[104:105]
	v_pk_mul_f32 v[106:107], v[102:103], v[106:107]
	v_pk_mul_f32 v[160:161], v[178:179], v[96:97] op_sel_hi:[0,1]
	v_pk_mul_f32 v[162:163], v[178:179], v[98:99] op_sel_hi:[0,1]
	v_exp_f32_e32 v160, v160
	v_exp_f32_e32 v161, v161
	v_exp_f32_e32 v162, v162
	v_exp_f32_e32 v163, v163
	v_pk_add_f32 v[160:161], v[178:179], v[160:161] op_sel:[1,0] op_sel_hi:[1,1]
	v_pk_add_f32 v[162:163], v[178:179], v[162:163] op_sel:[1,0] op_sel_hi:[1,1]
	v_rcp_f32_e32 v160, v160
	v_rcp_f32_e32 v161, v161
	v_rcp_f32_e32 v162, v162
	v_rcp_f32_e32 v163, v163
	v_pk_mul_f32 v[96:97], v[96:97], v[160:161]
	v_pk_mul_f32 v[98:99], v[98:99], v[162:163]
	v_pk_mul_f32 v[96:97], v[92:93], v[96:97]
	v_pk_mul_f32 v[98:99], v[94:95], v[98:99]
	v_cvt_pk_bf16_f32 v104, v104, v105
	v_cvt_pk_bf16_f32 v105, v106, v107
	v_cvt_pk_bf16_f32 v106, v96, v97
	v_cvt_pk_bf16_f32 v107, v98, v99
	v_add_u32_e32 v187, 0xac000, v186
	global_store_dwordx4 v187, v[104:107], s[14:15] sc0 sc1
	v_pk_mul_f32 v[88:89], v[172:173], v[88:89] op_sel_hi:[0,1]
	v_pk_mul_f32 v[84:85], v[172:173], v[84:85] op_sel_hi:[0,1]
	v_pk_mul_f32 v[90:91], v[172:173], v[90:91] op_sel_hi:[0,1]
	v_pk_mul_f32 v[86:87], v[172:173], v[86:87] op_sel_hi:[0,1]
	v_pk_mul_f32 v[80:81], v[172:173], v[80:81] op_sel_hi:[0,1]
	v_pk_mul_f32 v[76:77], v[172:173], v[76:77] op_sel_hi:[0,1]
	v_pk_mul_f32 v[82:83], v[172:173], v[82:83] op_sel_hi:[0,1]
	v_pk_mul_f32 v[78:79], v[172:173], v[78:79] op_sel_hi:[0,1]
	v_pk_mul_f32 v[88:89], v[44:45], v[88:89]
	v_pk_mul_f32 v[84:85], v[144:145], v[84:85]
	v_pk_mul_f32 v[90:91], v[46:47], v[90:91]
	v_pk_mul_f32 v[86:87], v[146:147], v[86:87]
	v_pk_mul_f32 v[80:81], v[36:37], v[80:81]
	v_pk_mul_f32 v[76:77], v[140:141], v[76:77]
	v_pk_mul_f32 v[82:83], v[38:39], v[82:83]
	v_pk_mul_f32 v[78:79], v[142:143], v[78:79]
	v_pk_mul_f32 v[160:161], v[178:179], v[88:89] op_sel_hi:[0,1]
	v_pk_mul_f32 v[162:163], v[178:179], v[90:91] op_sel_hi:[0,1]
	v_exp_f32_e32 v160, v160
	v_exp_f32_e32 v161, v161
	v_exp_f32_e32 v162, v162
	v_exp_f32_e32 v163, v163
	v_pk_add_f32 v[160:161], v[178:179], v[160:161] op_sel:[1,0] op_sel_hi:[1,1]
	v_pk_add_f32 v[162:163], v[178:179], v[162:163] op_sel:[1,0] op_sel_hi:[1,1]
	v_rcp_f32_e32 v160, v160
	v_rcp_f32_e32 v161, v161
	v_rcp_f32_e32 v162, v162
	v_rcp_f32_e32 v163, v163
	v_pk_mul_f32 v[88:89], v[88:89], v[160:161]
	v_pk_mul_f32 v[90:91], v[90:91], v[162:163]
	v_pk_mul_f32 v[88:89], v[84:85], v[88:89]
	v_pk_mul_f32 v[90:91], v[86:87], v[90:91]
	v_pk_mul_f32 v[160:161], v[178:179], v[80:81] op_sel_hi:[0,1]
	v_pk_mul_f32 v[162:163], v[178:179], v[82:83] op_sel_hi:[0,1]
	v_exp_f32_e32 v160, v160
	v_exp_f32_e32 v161, v161
	v_exp_f32_e32 v162, v162
	v_exp_f32_e32 v163, v163
	v_pk_add_f32 v[160:161], v[178:179], v[160:161] op_sel:[1,0] op_sel_hi:[1,1]
	v_pk_add_f32 v[162:163], v[178:179], v[162:163] op_sel:[1,0] op_sel_hi:[1,1]
	v_rcp_f32_e32 v160, v160
	v_rcp_f32_e32 v161, v161
	v_rcp_f32_e32 v162, v162
	v_rcp_f32_e32 v163, v163
	v_pk_mul_f32 v[80:81], v[80:81], v[160:161]
	v_pk_mul_f32 v[82:83], v[82:83], v[162:163]
	v_pk_mul_f32 v[80:81], v[76:77], v[80:81]
	v_pk_mul_f32 v[82:83], v[78:79], v[82:83]
	v_cvt_pk_bf16_f32 v88, v88, v89
	v_cvt_pk_bf16_f32 v89, v90, v91
	v_cvt_pk_bf16_f32 v90, v80, v81
	v_cvt_pk_bf16_f32 v91, v82, v83
	v_add_u32_e32 v187, 0x102000, v186
	global_store_dwordx4 v187, v[88:91], s[14:15] sc0 sc1
	v_pk_mul_f32 v[72:73], v[170:171], v[72:73] op_sel_hi:[0,1]
	v_pk_mul_f32 v[68:69], v[170:171], v[68:69] op_sel_hi:[0,1]
	v_pk_mul_f32 v[74:75], v[170:171], v[74:75] op_sel_hi:[0,1]
	v_pk_mul_f32 v[70:71], v[170:171], v[70:71] op_sel_hi:[0,1]
	v_pk_mul_f32 v[64:65], v[170:171], v[64:65] op_sel_hi:[0,1]
	v_pk_mul_f32 v[60:61], v[170:171], v[60:61] op_sel_hi:[0,1]
	v_pk_mul_f32 v[66:67], v[170:171], v[66:67] op_sel_hi:[0,1]
	v_pk_mul_f32 v[62:63], v[170:171], v[62:63] op_sel_hi:[0,1]
	v_pk_mul_f32 v[72:73], v[44:45], v[72:73]
	v_pk_mul_f32 v[68:69], v[144:145], v[68:69]
	v_pk_mul_f32 v[74:75], v[46:47], v[74:75]
	v_pk_mul_f32 v[70:71], v[146:147], v[70:71]
	v_pk_mul_f32 v[64:65], v[36:37], v[64:65]
	v_pk_mul_f32 v[60:61], v[140:141], v[60:61]
	v_pk_mul_f32 v[66:67], v[38:39], v[66:67]
	v_pk_mul_f32 v[62:63], v[142:143], v[62:63]
	v_pk_mul_f32 v[160:161], v[178:179], v[72:73] op_sel_hi:[0,1]
	v_pk_mul_f32 v[162:163], v[178:179], v[74:75] op_sel_hi:[0,1]
	v_exp_f32_e32 v160, v160
	v_exp_f32_e32 v161, v161
	v_exp_f32_e32 v162, v162
	v_exp_f32_e32 v163, v163
	v_pk_add_f32 v[160:161], v[178:179], v[160:161] op_sel:[1,0] op_sel_hi:[1,1]
	v_pk_add_f32 v[162:163], v[178:179], v[162:163] op_sel:[1,0] op_sel_hi:[1,1]
	v_rcp_f32_e32 v160, v160
	v_rcp_f32_e32 v161, v161
	v_rcp_f32_e32 v162, v162
	v_rcp_f32_e32 v163, v163
	v_pk_mul_f32 v[72:73], v[72:73], v[160:161]
	v_pk_mul_f32 v[74:75], v[74:75], v[162:163]
; __device__ __forceinline__ unsigned cvt_pk_bf16(float lo, float hi) { unsigned r; asm volatile("v_cvt_pk_bf16_f32 %0, %1, %2" : "=v"(r) : "v"(lo), "v"(hi)); return r; }
; __device__ __forceinline__ float fast_sigmoid(float x) { return __builtin_amdgcn_rcpf(1.0f + __expf(-x)); }
;     __device__ __forceinline__ void operator()(const i32x4 (&acc)[2][2][4][2], const Unit& u, int wr, int wc, int fr, int fq) const {
;     ...
;         for (int ai = 0; ai < 2; ++ai)
; #pragma unroll
;             for (int m = 0; m < 4; ++m) { const int row = row0 + ai * HALF + m * 16; const float ra = rav[ai][m]; bf16_t* rowp = H + (size_t)row * ldh + col0;
;                 float hv[8];
; #pragma unroll
;                 for (int j = 0; j < 4; ++j) { const float g0 = (float)acc[ai][0][m][0][j] * ra * dg0[j], u0 = (float)acc[ai][1][m][0][j] * ra * du0[j]; hv[j] = g0 * fast_sigmoid(g0) * u0;
;                     const float g1 = (float)acc[ai][0][m][1][j] * ra * dg1[j], u1 = (float)acc[ai][1][m][1][j] * ra * du1[j]; hv[4 + j] = g1 * fast_sigmoid(g1) * u1; }
;                 u32x4 w; w.x = cvt_pk_bf16(hv[0], hv[1]); w.y = cvt_pk_bf16(hv[2], hv[3]); w.z = cvt_pk_bf16(hv[4], hv[5]); w.w = cvt_pk_bf16(hv[6], hv[7]);
;                 *(u32x4*)rowp = w; }
	v_pk_mul_f32 v[72:73], v[68:69], v[72:73]
	v_pk_mul_f32 v[74:75], v[70:71], v[74:75]
	v_pk_mul_f32 v[160:161], v[178:179], v[64:65] op_sel_hi:[0,1]
	v_pk_mul_f32 v[162:163], v[178:179], v[66:67] op_sel_hi:[0,1]
	v_exp_f32_e32 v160, v160
	v_exp_f32_e32 v161, v161
	v_exp_f32_e32 v162, v162
	v_exp_f32_e32 v163, v163
	v_pk_add_f32 v[160:161], v[178:179], v[160:161] op_sel:[1,0] op_sel_hi:[1,1]
	v_pk_add_f32 v[162:163], v[178:179], v[162:163] op_sel:[1,0] op_sel_hi:[1,1]
	v_rcp_f32_e32 v160, v160
	v_rcp_f32_e32 v161, v161
	v_rcp_f32_e32 v162, v162
	v_rcp_f32_e32 v163, v163
	v_pk_mul_f32 v[64:65], v[64:65], v[160:161]
	v_pk_mul_f32 v[66:67], v[66:67], v[162:163]
	v_pk_mul_f32 v[64:65], v[60:61], v[64:65]
	v_pk_mul_f32 v[66:67], v[62:63], v[66:67]
	v_cvt_pk_bf16_f32 v72, v72, v73
	v_cvt_pk_bf16_f32 v73, v74, v75
	v_cvt_pk_bf16_f32 v74, v64, v65
	v_cvt_pk_bf16_f32 v75, v66, v67
	v_add_u32_e32 v187, 0x2b0000, v186
	global_store_dwordx4 v187, v[72:75], s[14:15] sc0 sc1
	v_pk_mul_f32 v[56:57], v[168:169], v[56:57] op_sel_hi:[0,1]
	v_pk_mul_f32 v[52:53], v[168:169], v[52:53] op_sel_hi:[0,1]
	v_pk_mul_f32 v[58:59], v[168:169], v[58:59] op_sel_hi:[0,1]
	v_pk_mul_f32 v[54:55], v[168:169], v[54:55] op_sel_hi:[0,1]
	v_pk_mul_f32 v[48:49], v[168:169], v[48:49] op_sel_hi:[0,1]
	v_pk_mul_f32 v[40:41], v[168:169], v[40:41] op_sel_hi:[0,1]
	v_pk_mul_f32 v[50:51], v[168:169], v[50:51] op_sel_hi:[0,1]
	v_pk_mul_f32 v[42:43], v[168:169], v[42:43] op_sel_hi:[0,1]
	v_pk_mul_f32 v[56:57], v[44:45], v[56:57]
	v_pk_mul_f32 v[52:53], v[144:145], v[52:53]
	v_pk_mul_f32 v[58:59], v[46:47], v[58:59]
	v_pk_mul_f32 v[54:55], v[146:147], v[54:55]
	v_pk_mul_f32 v[48:49], v[36:37], v[48:49]
	v_pk_mul_f32 v[40:41], v[140:141], v[40:41]
	v_pk_mul_f32 v[50:51], v[38:39], v[50:51]
	v_pk_mul_f32 v[42:43], v[142:143], v[42:43]
	v_pk_mul_f32 v[160:161], v[178:179], v[56:57] op_sel_hi:[0,1]
	v_pk_mul_f32 v[162:163], v[178:179], v[58:59] op_sel_hi:[0,1]
	v_exp_f32_e32 v160, v160
	v_exp_f32_e32 v161, v161
	v_exp_f32_e32 v162, v162
	v_exp_f32_e32 v163, v163
	v_pk_add_f32 v[160:161], v[178:179], v[160:161] op_sel:[1,0] op_sel_hi:[1,1]
	v_pk_add_f32 v[162:163], v[178:179], v[162:163] op_sel:[1,0] op_sel_hi:[1,1]
	v_rcp_f32_e32 v160, v160
	v_rcp_f32_e32 v161, v161
	v_rcp_f32_e32 v162, v162
	v_rcp_f32_e32 v163, v163
	v_pk_mul_f32 v[56:57], v[56:57], v[160:161]
	v_pk_mul_f32 v[58:59], v[58:59], v[162:163]
	v_pk_mul_f32 v[56:57], v[52:53], v[56:57]
	v_pk_mul_f32 v[58:59], v[54:55], v[58:59]
	v_pk_mul_f32 v[160:161], v[178:179], v[48:49] op_sel_hi:[0,1]
	v_pk_mul_f32 v[162:163], v[178:179], v[50:51] op_sel_hi:[0,1]
	v_exp_f32_e32 v160, v160
	v_exp_f32_e32 v161, v161
	v_exp_f32_e32 v162, v162
	v_exp_f32_e32 v163, v163
	v_pk_add_f32 v[160:161], v[178:179], v[160:161] op_sel:[1,0] op_sel_hi:[1,1]
	v_pk_add_f32 v[162:163], v[178:179], v[162:163] op_sel:[1,0] op_sel_hi:[1,1]
	v_rcp_f32_e32 v160, v160
	v_rcp_f32_e32 v161, v161
	v_rcp_f32_e32 v162, v162
	v_rcp_f32_e32 v163, v163
	v_pk_mul_f32 v[48:49], v[48:49], v[160:161]
	v_pk_mul_f32 v[50:51], v[50:51], v[162:163]
	v_pk_mul_f32 v[48:49], v[40:41], v[48:49]
	v_pk_mul_f32 v[50:51], v[42:43], v[50:51]
	v_cvt_pk_bf16_f32 v56, v56, v57
	v_cvt_pk_bf16_f32 v57, v58, v59
	v_cvt_pk_bf16_f32 v58, v48, v49
	v_cvt_pk_bf16_f32 v59, v50, v51
	v_add_u32_e32 v187, 0x306000, v186
	global_store_dwordx4 v187, v[56:59], s[14:15] sc0 sc1
	v_pk_mul_f32 v[32:33], v[166:167], v[32:33] op_sel_hi:[0,1]
	v_pk_mul_f32 v[28:29], v[166:167], v[28:29] op_sel_hi:[0,1]
	v_pk_mul_f32 v[34:35], v[166:167], v[34:35] op_sel_hi:[0,1]
	v_pk_mul_f32 v[30:31], v[166:167], v[30:31] op_sel_hi:[0,1]
	v_pk_mul_f32 v[24:25], v[166:167], v[24:25] op_sel_hi:[0,1]
	v_pk_mul_f32 v[20:21], v[166:167], v[20:21] op_sel_hi:[0,1]
	v_pk_mul_f32 v[26:27], v[166:167], v[26:27] op_sel_hi:[0,1]
	v_pk_mul_f32 v[22:23], v[166:167], v[22:23] op_sel_hi:[0,1]
	v_pk_mul_f32 v[32:33], v[44:45], v[32:33]
	v_pk_mul_f32 v[28:29], v[144:145], v[28:29]
	v_pk_mul_f32 v[34:35], v[46:47], v[34:35]
	v_pk_mul_f32 v[30:31], v[146:147], v[30:31]
	v_pk_mul_f32 v[24:25], v[36:37], v[24:25]
	v_pk_mul_f32 v[20:21], v[140:141], v[20:21]
	v_pk_mul_f32 v[26:27], v[38:39], v[26:27]
; __device__ __forceinline__ unsigned cvt_pk_bf16(float lo, float hi) { unsigned r; asm volatile("v_cvt_pk_bf16_f32 %0, %1, %2" : "=v"(r) : "v"(lo), "v"(hi)); return r; }
; __device__ __forceinline__ float fast_sigmoid(float x) { return __builtin_amdgcn_rcpf(1.0f + __expf(-x)); }
; #define PG8_BAR __builtin_amdgcn_s_barrier()
;     __device__ __forceinline__ void operator()(const i32x4 (&acc)[2][2][4][2], const Unit& u, int wr, int wc, int fr, int fq) const {
;     ...
;                 for (int j = 0; j < 4; ++j) { const float g0 = (float)acc[ai][0][m][0][j] * ra * dg0[j], u0 = (float)acc[ai][1][m][0][j] * ra * du0[j]; hv[j] = g0 * fast_sigmoid(g0) * u0;
;                     const float g1 = (float)acc[ai][0][m][1][j] * ra * dg1[j], u1 = (float)acc[ai][1][m][1][j] * ra * du1[j]; hv[4 + j] = g1 * fast_sigmoid(g1) * u1; }
;                 u32x4 w; w.x = cvt_pk_bf16(hv[0], hv[1]); w.y = cvt_pk_bf16(hv[2], hv[3]); w.z = cvt_pk_bf16(hv[4], hv[5]); w.w = cvt_pk_bf16(hv[6], hv[7]);
;                 *(u32x4*)rowp = w; }
; template <class Epi, class Sched, bool ALIGN_EPI = false, bool SP2 = false, bool I8 = false>
; __device__ __forceinline__ void gemm_phase(PG8_LAS unsigned char* lds, const Gemm g, const Sched& S, const Epi& E) {
;     ...
;         if (!has_next) break;
; #pragma unroll
;         for (int a = 0; a < 2; ++a)
; #pragma unroll
;             for (int b = 0; b < 2; ++b)
; #pragma unroll
;                 for (int m = 0; m < 4; ++m)
; #pragma unroll
;                     for (int n = 0; n < 2; ++n) acc[a][b][m][n] = (acc_t){0, 0, 0, 0};
;         cur = nxt; cA = nA; cB = nB; ++ui;
;         if constexpr (ALIGN_EPI) { if (wr == 1) PG8_BAR; }
	v_pk_mul_f32 v[22:23], v[142:143], v[22:23]
	v_pk_mul_f32 v[160:161], v[178:179], v[32:33] op_sel_hi:[0,1]
	v_pk_mul_f32 v[162:163], v[178:179], v[34:35] op_sel_hi:[0,1]
	v_exp_f32_e32 v160, v160
	v_exp_f32_e32 v161, v161
	v_exp_f32_e32 v162, v162
	v_exp_f32_e32 v163, v163
	v_pk_add_f32 v[160:161], v[178:179], v[160:161] op_sel:[1,0] op_sel_hi:[1,1]
	v_pk_add_f32 v[162:163], v[178:179], v[162:163] op_sel:[1,0] op_sel_hi:[1,1]
	v_rcp_f32_e32 v160, v160
	v_rcp_f32_e32 v161, v161
	v_rcp_f32_e32 v162, v162
	v_rcp_f32_e32 v163, v163
	v_pk_mul_f32 v[32:33], v[32:33], v[160:161]
	v_pk_mul_f32 v[34:35], v[34:35], v[162:163]
	v_pk_mul_f32 v[32:33], v[28:29], v[32:33]
	v_pk_mul_f32 v[34:35], v[30:31], v[34:35]
	v_pk_mul_f32 v[160:161], v[178:179], v[24:25] op_sel_hi:[0,1]
	v_pk_mul_f32 v[162:163], v[178:179], v[26:27] op_sel_hi:[0,1]
	v_exp_f32_e32 v160, v160
	v_exp_f32_e32 v161, v161
	v_exp_f32_e32 v162, v162
	v_exp_f32_e32 v163, v163
	v_pk_add_f32 v[160:161], v[178:179], v[160:161] op_sel:[1,0] op_sel_hi:[1,1]
	v_pk_add_f32 v[162:163], v[178:179], v[162:163] op_sel:[1,0] op_sel_hi:[1,1]
	v_rcp_f32_e32 v160, v160
	v_rcp_f32_e32 v161, v161
	v_rcp_f32_e32 v162, v162
	v_rcp_f32_e32 v163, v163
	v_pk_mul_f32 v[24:25], v[24:25], v[160:161]
	v_pk_mul_f32 v[26:27], v[26:27], v[162:163]
	v_pk_mul_f32 v[24:25], v[20:21], v[24:25]
	v_pk_mul_f32 v[26:27], v[22:23], v[26:27]
	v_cvt_pk_bf16_f32 v32, v32, v33
	v_cvt_pk_bf16_f32 v33, v34, v35
	v_cvt_pk_bf16_f32 v34, v24, v25
	v_cvt_pk_bf16_f32 v35, v26, v27
	v_add_u32_e32 v187, 0x35c000, v186
	global_store_dwordx4 v187, v[32:35], s[14:15] sc0 sc1
	v_pk_mul_f32 v[16:17], v[158:159], v[16:17] op_sel_hi:[0,1]
	v_pk_mul_f32 v[12:13], v[158:159], v[12:13] op_sel_hi:[0,1]
	v_pk_mul_f32 v[18:19], v[158:159], v[18:19] op_sel_hi:[0,1]
	v_pk_mul_f32 v[14:15], v[158:159], v[14:15] op_sel_hi:[0,1]
	v_pk_mul_f32 v[8:9], v[158:159], v[8:9] op_sel_hi:[0,1]
	v_pk_mul_f32 v[4:5], v[158:159], v[4:5] op_sel_hi:[0,1]
	v_pk_mul_f32 v[10:11], v[158:159], v[10:11] op_sel_hi:[0,1]
	v_pk_mul_f32 v[6:7], v[158:159], v[6:7] op_sel_hi:[0,1]
	v_pk_mul_f32 v[16:17], v[44:45], v[16:17]
	v_pk_mul_f32 v[12:13], v[144:145], v[12:13]
	v_pk_mul_f32 v[18:19], v[46:47], v[18:19]
	v_pk_mul_f32 v[14:15], v[146:147], v[14:15]
	v_pk_mul_f32 v[8:9], v[36:37], v[8:9]
	v_pk_mul_f32 v[4:5], v[140:141], v[4:5]
	v_pk_mul_f32 v[10:11], v[38:39], v[10:11]
	v_pk_mul_f32 v[6:7], v[142:143], v[6:7]
	v_pk_mul_f32 v[160:161], v[178:179], v[16:17] op_sel_hi:[0,1]
	v_pk_mul_f32 v[162:163], v[178:179], v[18:19] op_sel_hi:[0,1]
	v_exp_f32_e32 v160, v160
	v_exp_f32_e32 v161, v161
	v_exp_f32_e32 v162, v162
	v_exp_f32_e32 v163, v163
	v_pk_add_f32 v[160:161], v[178:179], v[160:161] op_sel:[1,0] op_sel_hi:[1,1]
	v_pk_add_f32 v[162:163], v[178:179], v[162:163] op_sel:[1,0] op_sel_hi:[1,1]
	v_rcp_f32_e32 v160, v160
	v_rcp_f32_e32 v161, v161
	v_rcp_f32_e32 v162, v162
	v_rcp_f32_e32 v163, v163
	v_pk_mul_f32 v[16:17], v[16:17], v[160:161]
	v_pk_mul_f32 v[18:19], v[18:19], v[162:163]
	v_pk_mul_f32 v[16:17], v[12:13], v[16:17]
	v_pk_mul_f32 v[18:19], v[14:15], v[18:19]
	v_pk_mul_f32 v[160:161], v[178:179], v[8:9] op_sel_hi:[0,1]
	v_pk_mul_f32 v[162:163], v[178:179], v[10:11] op_sel_hi:[0,1]
	v_exp_f32_e32 v160, v160
	v_exp_f32_e32 v161, v161
	v_exp_f32_e32 v162, v162
	v_exp_f32_e32 v163, v163
	v_pk_add_f32 v[160:161], v[178:179], v[160:161] op_sel:[1,0] op_sel_hi:[1,1]
	v_pk_add_f32 v[162:163], v[178:179], v[162:163] op_sel:[1,0] op_sel_hi:[1,1]
	v_rcp_f32_e32 v160, v160
	v_rcp_f32_e32 v161, v161
	v_rcp_f32_e32 v162, v162
	v_rcp_f32_e32 v163, v163
	v_pk_mul_f32 v[8:9], v[8:9], v[160:161]
	v_pk_mul_f32 v[10:11], v[10:11], v[162:163]
	v_pk_mul_f32 v[8:9], v[4:5], v[8:9]
	v_pk_mul_f32 v[10:11], v[6:7], v[10:11]
	v_cvt_pk_bf16_f32 v16, v16, v17
	v_cvt_pk_bf16_f32 v17, v18, v19
	v_cvt_pk_bf16_f32 v18, v8, v9
	v_cvt_pk_bf16_f32 v19, v10, v11
	v_add_u32_e32 v187, 0x3b2000, v186
	global_store_dwordx4 v187, v[16:19], s[14:15] sc0 sc1
	s_mov_b32 s67, 0x40000
	s_mov_b64 s[34:35], -1
	s_andn2_b64 vcc, exec, s[10:11]
	s_cbranch_vccnz .LBB0_1587
	s_andn2_b64 vcc, exec, s[12:13]
	s_cbranch_vccnz .LBB0_1586
	s_barrier
	s_branch .LBB0_1586
